# v11 plus transposed-reversed row-tile mapping in P1 and P5
# baseline (speedup 1.0000x reference)
; #define RUN(k) (PH_ON(k) && p.ph_lo <= (k) && (k) <= p.ph_hi)
;     __device__ bool next(int i, Unit& u) const {
;         const long L = (long)i * G + c; if (L >= nwg) return false;
;         int wgid = (int)L; { const int q = nwg / NXCD, r = nwg % NXCD, xcd = wgid % NXCD, off = wgid / NXCD; wgid = (xcd < r ? xcd * (q + 1) : r * (q + 1) + (xcd - r) * q) + off; }
;         const int nig = WGM * nN, gid = wgid / nig, fm = gid * WGM, gsz = (nM - fm) < WGM ? (nM - fm) : WGM;
;         const int pm = fm + ((wgid % nig) % gsz), pn = (wgid % nig) / gsz;
;         u.pm = pm; u.pn = pn;
;         if (mode == 0) { u.aoff = (size_t)pm * 256 * lda2; u.boff = (size_t)pn * 256 * ldb2; }
;         else if (mode == 3) { const int b = pm >> 2, h = pm & 3; u.aoff = (size_t)(b * 256) * lda2 + (size_t)h * 1024; u.boff = (size_t)pn * 256 * ldb2 + (size_t)h * 1024; }
; __global__ void __launch_bounds__(512) fwd_megakernel(Params p) {
;     ...
;     if (RUN(1)) {
;         { pg8::Gemm g{H, (const bf16_t*)(ws + WS_WIN), D, D, D}; pg8::Order S; S.init(vcu, T / 256, INC / 256, 0, D, D);
;           pg8::EpiIn E{B0, (float*)(ws + WS_LOGF), (const float*)(ws + WS_LB)}; pg8::gemm_phase(lds, g, S, E); }
.LBB0_124:
	s_add_u32 s44, s72, 0xc400000
	s_addc_u32 s45, s73, 0
	s_cmp_lt_i32 s74, 2
	s_cselect_b64 s[14:15], -1, 0
	s_and_b64 s[0:1], s[14:15], s[20:21]
	s_andn2_b64 vcc, exec, s[0:1]
	v_readfirstlane_b32 s0, v0
	s_nop 1
	v_writelane_b32 v250, s0, 41
	s_cbranch_vccnz .LBB0_179
	s_load_dword s3, s[96:97], 0xc0
	v_readlane_b32 s2, v250, 41
	s_waitcnt lgkmcnt(0)
	v_cvt_f32_u32_e32 v0, s3
	s_sub_i32 s0, 0, s3
	v_rcp_iflag_f32_e32 v0, v0
	s_nop 0
	v_mul_f32_e32 v0, 0x4f7ffffe, v0
	v_cvt_u32_f32_e32 v0, v0
	s_nop 0
	v_readfirstlane_b32 s1, v0
	s_mul_i32 s0, s0, s1
	s_mul_hi_u32 s0, s1, s0
	s_add_i32 s1, s1, s0
	s_mul_hi_u32 s0, s2, s1
	s_mul_i32 s0, s0, s3
	s_sub_i32 s0, s2, s0
	s_sub_i32 s1, s0, s3
	s_cmp_ge_u32 s0, s3
	s_cselect_b32 s0, s1, s0
	s_sub_i32 s1, s0, s3
	s_cmp_ge_u32 s0, s3
	s_cselect_b32 s42, s1, s0
	s_cmpk_lt_i32 s42, 0xe00
	s_cselect_b64 s[8:9], -1, 0
	s_cmpk_gt_i32 s42, 0xdff
	v_readfirstlane_b32 s1, v206
	s_cbranch_scc1 .LBB0_127
	s_ashr_i32 s0, s42, 31
	s_lshr_b32 s0, s0, 29
	s_add_i32 s0, s42, s0
	s_ashr_i32 s2, s0, 3
	s_and_b32 s0, s0, -8
	s_sub_i32 s0, s42, s0
	s_cmp_lt_i32 s0, 0
	s_movk_i32 s4, 0x1c1
	s_cselect_b32 s4, s4, 0x1c0
	s_mul_i32 s0, s0, s4
	s_add_i32 s0, s0, s2
	s_mul_hi_i32 s2, s0, 0x92492493
	s_add_i32 s2, s2, s0
	s_lshr_b32 s4, s2, 31
	s_ashr_i32 s2, s2, 6
	s_add_i32 s2, s2, s4
	s_lshl_b32 s4, s2, 2
	s_mulk_i32 s2, 0x70
	s_sub_i32 s0, s0, s2
	s_bfe_i32 s2, s0, 0x80000
	s_bfe_u32 s2, s2, 0x2000d
	s_add_i32 s5, s0, s2
	s_bfe_i32 s2, s5, 0x80000
	s_and_b32 s5, s5, 0xfc
	s_sub_i32 s0, s0, s5
	s_sext_i32_i16 s7, s2
	s_sext_i32_i8 s0, s0
	s_lshr_b32 s2, s7, 2
	s_add_i32 s6, s4, s0
	s_and_b32 s98, s6, 15
	s_lshl_b32 s98, s98, 3
	s_lshr_b32 s99, s6, 4
	s_add_i32 s6, s98, s99
	s_sub_i32 s6, 0x7f, s6
	s_ashr_i32 s0, s7, 2
	s_ashr_i32 s7, s6, 31
	s_bfe_i64 s[10:11], s[2:3], 0x100000
	s_lshl_b64 s[4:5], s[6:7], 20
	s_lshl_b64 s[10:11], s[10:11], 20
	s_andn2_b64 vcc, exec, s[8:9]
	s_cbranch_vccz .LBB0_128
	s_branch .LBB0_179

;     __device__ bool next(int i, Unit& u) const {
;     ...
;         int wgid = (int)L; { const int q = nwg / NXCD, r = nwg % NXCD, xcd = wgid % NXCD, off = wgid / NXCD; wgid = (xcd < r ? xcd * (q + 1) : r * (q + 1) + (xcd - r) * q) + off; }
;         const int nig = WGM * nN, gid = wgid / nig, fm = gid * WGM, gsz = (nM - fm) < WGM ? (nM - fm) : WGM;
;         const int pm = fm + ((wgid % nig) % gsz), pn = (wgid % nig) / gsz;
;         u.pm = pm; u.pn = pn;
;         if (mode == 0) { u.aoff = (size_t)pm * 256 * lda2; u.boff = (size_t)pn * 256 * ldb2; }
.LBB0_133:
	s_add_i32 s50, s50, 1
	s_mul_i32 s1, s50, s55
	s_mul_hi_u32 s2, s50, s3
	s_add_i32 s2, s2, s1
	s_mul_i32 s1, s50, s3
	s_add_u32 s12, s1, s42
	s_addc_u32 s13, s2, s56
	v_cmp_gt_i64_e32 vcc, s[12:13], v[152:153]
	v_cmp_lt_i64_e64 s[4:5], s[12:13], v[150:151]
	s_cbranch_vccnz .LBB0_135
	s_ashr_i32 s1, s12, 31
	s_lshr_b32 s1, s1, 29
	s_add_i32 s1, s12, s1
	s_ashr_i32 s2, s1, 3
	s_and_b32 s1, s1, -8
	s_sub_i32 s1, s12, s1
	s_cmp_lt_i32 s1, 0
	s_movk_i32 s7, 0x1c1
	s_cselect_b32 s7, s7, 0x1c0
	s_mul_i32 s1, s1, s7
	s_add_i32 s1, s1, s2
	s_mul_hi_i32 s2, s1, 0x92492493
	s_add_i32 s2, s2, s1
	s_lshr_b32 s7, s2, 31
	s_ashr_i32 s2, s2, 6
	s_add_i32 s2, s2, s7
	s_lshl_b32 s7, s2, 2
	s_sub_i32 s12, 0x80, s7
	s_min_i32 s12, s12, 4
	s_abs_i32 s13, s12
	v_cvt_f32_u32_e32 v0, s13
	s_sub_i32 s29, 0, s13
	s_mulk_i32 s2, 0x70
	s_sub_i32 s1, s1, s2
	v_rcp_iflag_f32_e32 v0, v0
	s_abs_i32 s2, s1
	s_xor_b32 s28, s1, s12
	s_ashr_i32 s28, s28, 31
	v_mul_f32_e32 v0, 0x4f7ffffe, v0
	v_cvt_u32_f32_e32 v0, v0
	s_nop 0
	v_readfirstlane_b32 s30, v0
	s_mul_i32 s29, s29, s30
	s_mul_hi_u32 s29, s30, s29
	s_add_i32 s30, s30, s29
	s_mul_hi_u32 s29, s2, s30
	s_mul_i32 s30, s29, s13
	s_sub_i32 s2, s2, s30
	s_add_i32 s31, s29, 1
	s_sub_i32 s30, s2, s13
	s_cmp_ge_u32 s2, s13
	s_cselect_b32 s29, s31, s29
	s_cselect_b32 s2, s30, s2
	s_add_i32 s30, s29, 1
	s_cmp_ge_u32 s2, s13
	s_cselect_b32 s2, s30, s29
	s_xor_b32 s2, s2, s28
	s_sub_i32 s28, s2, s28
	s_mul_i32 s2, s28, s12
	s_sub_i32 s1, s1, s2
	s_add_i32 s30, s7, s1
	s_and_b32 s98, s30, 15
	s_lshl_b32 s98, s98, 3
	s_lshr_b32 s99, s30, 4
	s_add_i32 s30, s98, s99
	s_sub_i32 s30, 0x7f, s30
	s_ashr_i32 s31, s30, 31
	s_ashr_i32 s29, s28, 31
	s_lshl_b64 s[34:35], s[30:31], 20
	s_lshl_b64 s[36:37], s[28:29], 20

;     __device__ bool next(int i, Unit& u) const {
;     ...
;         int wgid = (int)L; { const int q = nwg / NXCD, r = nwg % NXCD, xcd = wgid % NXCD, off = wgid / NXCD; wgid = (xcd < r ? xcd * (q + 1) : r * (q + 1) + (xcd - r) * q) + off; }
;         const int nig = WGM * nN, gid = wgid / nig, fm = gid * WGM, gsz = (nM - fm) < WGM ? (nM - fm) : WGM;
;         const int pm = fm + ((wgid % nig) % gsz), pn = (wgid % nig) / gsz;
;         u.pm = pm; u.pn = pn;
;         if (mode == 0) { u.aoff = (size_t)pm * 256 * lda2; u.boff = (size_t)pn * 256 * ldb2; }
.LBB0_526:
	s_add_i32 s2, s3, s4
	s_ashr_i32 s3, s2, 31
	s_lshr_b32 s3, s3, 27
	s_add_i32 s3, s2, s3
	s_ashr_i32 s4, s3, 5
	s_and_b32 s3, s3, 0xffe0
	s_sub_i32 s3, s2, s3
	s_bfe_i32 s2, s3, 0x80000
	s_bfe_u32 s2, s2, 0x2000d
	s_add_i32 s5, s3, s2
	s_bfe_i32 s2, s5, 0x80000
	s_and_b32 s5, s5, 0xfc
	s_sub_i32 s3, s3, s5
	s_lshl_b32 s4, s4, 2
	s_sext_i32_i16 s10, s2
	s_sext_i32_i8 s3, s3
	s_lshr_b32 s2, s10, 2
	s_add_i32 s28, s4, s3
	s_and_b32 s98, s28, 15
	s_lshl_b32 s98, s98, 3
	s_lshr_b32 s99, s28, 4
	s_add_i32 s28, s98, s99
	s_sub_i32 s28, 0x7f, s28
	s_ashr_i32 s29, s28, 31
	s_bfe_i64 s[2:3], s[2:3], 0x100000
	s_ashr_i32 s51, s10, 2
	s_lshl_b64 s[4:5], s[28:29], 20
	s_lshl_b64 s[10:11], s[2:3], 20
	s_andn2_b64 vcc, exec, s[6:7]
	s_cbranch_vccnz .LBB0_562

;     __device__ bool next(int i, Unit& u) const {
;     ...
;         int wgid = (int)L; { const int q = nwg / NXCD, r = nwg % NXCD, xcd = wgid % NXCD, off = wgid / NXCD; wgid = (xcd < r ? xcd * (q + 1) : r * (q + 1) + (xcd - r) * q) + off; }
;         const int nig = WGM * nN, gid = wgid / nig, fm = gid * WGM, gsz = (nM - fm) < WGM ? (nM - fm) : WGM;
;         const int pm = fm + ((wgid % nig) % gsz), pn = (wgid % nig) / gsz;
;         u.pm = pm; u.pn = pn;
;         if (mode == 0) { u.aoff = (size_t)pm * 256 * lda2; u.boff = (size_t)pn * 256 * ldb2; }
.LBB0_537:
	s_ashr_i32 s16, s18, 3
	s_add_i32 s16, s20, s16
	s_ashr_i32 s17, s16, 31
	s_lshr_b32 s17, s17, 27
	s_add_i32 s17, s16, s17
	s_ashr_i32 s18, s17, 5
	s_lshl_b32 s18, s18, 2
	s_sub_i32 s19, 0x80, s18
	s_min_i32 s19, s19, 4
	s_abs_i32 s20, s19
	v_cvt_f32_u32_e32 v0, s20
	s_sub_i32 s22, 0, s20
	s_andn2_b32 s17, s17, 31
	s_sub_i32 s21, s16, s17
	v_rcp_iflag_f32_e32 v0, v0
	s_abs_i32 s16, s21
	s_xor_b32 s17, s21, s19
	s_ashr_i32 s17, s17, 31
	v_mul_f32_e32 v0, 0x4f7ffffe, v0
	v_cvt_u32_f32_e32 v0, v0
	s_nop 0
	v_readfirstlane_b32 s23, v0
	s_mul_i32 s22, s22, s23
	s_mul_hi_u32 s22, s23, s22
	s_add_i32 s23, s23, s22
	s_mul_hi_u32 s22, s16, s23
	s_mul_i32 s23, s22, s20
	s_sub_i32 s16, s16, s23
	s_add_i32 s24, s22, 1
	s_sub_i32 s23, s16, s20
	s_cmp_ge_u32 s16, s20
	s_cselect_b32 s22, s24, s22
	s_cselect_b32 s16, s23, s16
	s_add_i32 s23, s22, 1
	s_cmp_ge_u32 s16, s20
	s_cselect_b32 s16, s23, s22
	s_xor_b32 s16, s16, s17
	s_sub_i32 s16, s16, s17
	s_mul_i32 s19, s16, s19
	s_sub_i32 s19, s21, s19
	s_add_i32 s18, s18, s19
	s_and_b32 s98, s18, 15
	s_lshl_b32 s98, s98, 3
	s_lshr_b32 s99, s18, 4
	s_add_i32 s18, s98, s99
	s_sub_i32 s18, 0x7f, s18
	s_ashr_i32 s17, s16, 31
	s_ashr_i32 s19, s18, 31
	s_lshl_b64 s[20:21], s[18:19], 20
	s_lshl_b64 s[22:23], s[16:17], 20
